# residual epilogues: each 8-load batch split into two 4-load halves (less HBM request burstiness)
# speedup vs baseline: 1.0033x; 1.0033x over previous
.LBB0_122:
	s_ashr_i32 s18, s57, 31
	s_sub_i32 s20, s57, 64
	s_cmp_gt_i32 s57, 63
	v_readlane_b32 s22, v255, 52
	s_cselect_b32 s19, 0, s18
	s_cselect_b32 s18, s20, s57
	v_readlane_b32 s23, v255, 53
	s_cselect_b32 s20, s23, s11
	s_cselect_b32 s21, s22, s10
	s_lshl_b64 s[18:19], s[18:19], 20
	s_add_u32 s18, s21, s18
	s_addc_u32 s19, s20, s19
	s_min_i32 s20, s57, 64
	s_lshr_b32 s20, s20, 4
	s_mulk_i32 s20, 0x1800
	s_ashr_i32 s21, s20, 31
	s_lshl_b64 s[20:21], s[20:21], 2
	v_mov_b32_e32 v156, v191
	s_add_u32 s20, s39, s20
	s_addc_u32 s21, s40, s21
	s_lshl_b32 s22, s56, 8
	v_lshrrev_b32_e32 v130, 2, v156
	v_and_or_b32 v130, v130, 12, s22
	v_or_b32_e32 v130, s43, v130
	v_and_or_b32 v188, v156, 15, s42
	v_ashrrev_i32_e32 v131, 31, v130
	v_or_b32_e32 v172, 16, v188
	v_lshlrev_b64 v[152:153], 2, v[130:131]
	v_ashrrev_i32_e32 v189, 31, v188
	v_ashrrev_i32_e32 v173, 31, v172
	v_lshl_add_u64 v[130:131], s[20:21], 0, v[152:153]
	v_lshl_add_u64 v[192:193], s[18:19], 0, v[152:153]
	v_lshlrev_b64 v[152:153], 12, v[188:189]
	v_lshlrev_b64 v[172:173], 12, v[172:173]
	v_lshl_add_u64 v[152:153], v[192:193], 0, v[152:153]
	v_lshl_add_u64 v[194:195], v[192:193], 0, v[172:173]
	global_load_dwordx4 v[142:145], v[130:131], off
	global_load_dwordx4 v[138:141], v[130:131], off offset:64
	global_load_dwordx4 v[134:137], v[130:131], off offset:512
	s_nop 0
	global_load_dwordx4 v[130:133], v[130:131], off offset:576
	s_nop 0
	global_load_dwordx4 v[156:159], v[152:153], off
	global_load_dwordx4 v[160:163], v[152:153], off offset:64
	global_load_dwordx4 v[164:167], v[152:153], off offset:512
	global_load_dwordx4 v[168:171], v[152:153], off offset:576
	s_waitcnt vmcnt(0)
	global_load_dwordx4 v[172:175], v[194:195], off
	global_load_dwordx4 v[176:179], v[194:195], off offset:64
	global_load_dwordx4 v[180:183], v[194:195], off offset:512
	global_load_dwordx4 v[184:187], v[194:195], off offset:576
	s_waitcnt vmcnt(0)
	v_pk_fma_f32 v[108:109], v[108:109], v[132:133], v[170:171]
	v_pk_fma_f32 v[106:107], v[106:107], v[130:131], v[168:169]
	global_store_dwordx4 v[152:153], v[106:109], off offset:576
	v_pk_fma_f32 v[128:129], v[128:129], v[144:145], v[158:159]
	v_pk_fma_f32 v[126:127], v[126:127], v[142:143], v[156:157]
	v_pk_fma_f32 v[108:109], v[120:121], v[144:145], v[174:175]
	v_pk_fma_f32 v[106:107], v[118:119], v[142:143], v[172:173]
	v_pk_fma_f32 v[124:125], v[124:125], v[140:141], v[162:163]
	v_pk_fma_f32 v[122:123], v[122:123], v[138:139], v[160:161]
	v_pk_fma_f32 v[116:117], v[116:117], v[136:137], v[166:167]
	v_pk_fma_f32 v[114:115], v[114:115], v[134:135], v[164:165]
	global_store_dwordx4 v[194:195], v[106:109], off
	v_pk_fma_f32 v[104:105], v[104:105], v[136:137], v[182:183]
	v_pk_fma_f32 v[102:103], v[102:103], v[134:135], v[180:181]
	v_pk_fma_f32 v[108:109], v[112:113], v[140:141], v[178:179]
	v_pk_fma_f32 v[106:107], v[110:111], v[138:139], v[176:177]
	v_pk_fma_f32 v[100:101], v[100:101], v[132:133], v[186:187]
	v_pk_fma_f32 v[98:99], v[98:99], v[130:131], v[184:185]
	global_store_dwordx4 v[152:153], v[126:129], off
	global_store_dwordx4 v[152:153], v[122:125], off offset:64
	global_store_dwordx4 v[152:153], v[114:117], off offset:512
	global_store_dwordx4 v[194:195], v[106:109], off offset:64
	global_store_dwordx4 v[194:195], v[102:105], off offset:512
	global_store_dwordx4 v[194:195], v[98:101], off offset:576
	s_nop 1
	v_or_b32_e32 v98, 32, v188
	v_or_b32_e32 v114, 48, v188
	v_ashrrev_i32_e32 v99, 31, v98
	v_ashrrev_i32_e32 v115, 31, v114
	v_lshlrev_b64 v[98:99], 12, v[98:99]
	v_lshlrev_b64 v[114:115], 12, v[114:115]
	v_lshl_add_u64 v[156:157], v[192:193], 0, v[98:99]
	v_lshl_add_u64 v[158:159], v[192:193], 0, v[114:115]
	global_load_dwordx4 v[98:101], v[156:157], off
	global_load_dwordx4 v[102:105], v[156:157], off offset:64
	global_load_dwordx4 v[106:109], v[156:157], off offset:512
	global_load_dwordx4 v[110:113], v[156:157], off offset:576
	s_waitcnt vmcnt(0)
	global_load_dwordx4 v[114:117], v[158:159], off
	global_load_dwordx4 v[118:121], v[158:159], off offset:64
	global_load_dwordx4 v[122:125], v[158:159], off offset:512
	global_load_dwordx4 v[126:129], v[158:159], off offset:576
	s_waitcnt vmcnt(4)
	v_pk_fma_f32 v[76:77], v[76:77], v[132:133], v[112:113]
	v_pk_fma_f32 v[74:75], v[74:75], v[130:131], v[110:111]
	global_store_dwordx4 v[156:157], v[74:77], off offset:576
	v_pk_fma_f32 v[96:97], v[96:97], v[144:145], v[100:101]
	v_pk_fma_f32 v[94:95], v[94:95], v[142:143], v[98:99]
	s_waitcnt vmcnt(4)
	v_pk_fma_f32 v[76:77], v[88:89], v[144:145], v[116:117]
	v_pk_fma_f32 v[74:75], v[86:87], v[142:143], v[114:115]
	v_pk_fma_f32 v[92:93], v[92:93], v[140:141], v[104:105]
	v_pk_fma_f32 v[90:91], v[90:91], v[138:139], v[102:103]
	v_pk_fma_f32 v[84:85], v[84:85], v[136:137], v[108:109]
	v_pk_fma_f32 v[82:83], v[82:83], v[134:135], v[106:107]
	global_store_dwordx4 v[158:159], v[74:77], off
	s_waitcnt vmcnt(3)
	v_pk_fma_f32 v[72:73], v[72:73], v[136:137], v[124:125]
	v_pk_fma_f32 v[70:71], v[70:71], v[134:135], v[122:123]
	v_pk_fma_f32 v[76:77], v[80:81], v[140:141], v[120:121]
	v_pk_fma_f32 v[74:75], v[78:79], v[138:139], v[118:119]
	s_waitcnt vmcnt(2)
	v_pk_fma_f32 v[68:69], v[68:69], v[132:133], v[128:129]
	v_pk_fma_f32 v[66:67], v[66:67], v[130:131], v[126:127]
	global_store_dwordx4 v[156:157], v[94:97], off
	global_store_dwordx4 v[156:157], v[90:93], off offset:64
	global_store_dwordx4 v[156:157], v[82:85], off offset:512
	global_store_dwordx4 v[158:159], v[74:77], off offset:64
	global_store_dwordx4 v[158:159], v[70:73], off offset:512
	global_store_dwordx4 v[158:159], v[66:69], off offset:576
	s_mov_b64 s[18:19], 0x80000
	v_lshl_add_u64 v[98:99], v[152:153], 0, s[18:19]
	s_mov_b32 s18, 0x80000
	v_add_co_u32_e32 v100, vcc, s18, v152
	s_mov_b64 s[18:19], 0x90000
	s_nop 0
	v_addc_co_u32_e32 v101, vcc, 0, v153, vcc
	v_lshl_add_u64 v[102:103], v[152:153], 0, s[18:19]
	v_add_co_u32_e32 v104, vcc, s80, v152
	global_load_dwordx4 v[66:69], v[98:99], off offset:64
	global_load_dwordx4 v[70:73], v[98:99], off offset:512
	global_load_dwordx4 v[74:77], v[100:101], off
	global_load_dwordx4 v[78:81], v[98:99], off offset:576
	v_addc_co_u32_e32 v105, vcc, 0, v153, vcc
	global_load_dwordx4 v[82:85], v[102:103], off offset:64
	global_load_dwordx4 v[86:89], v[102:103], off offset:512
	global_load_dwordx4 v[90:93], v[104:105], off
	global_load_dwordx4 v[94:97], v[102:103], off offset:576
	s_waitcnt vmcnt(4)
	v_pk_fma_f32 v[44:45], v[44:45], v[132:133], v[80:81]
	v_pk_fma_f32 v[42:43], v[42:43], v[130:131], v[78:79]
	global_store_dwordx4 v[98:99], v[42:45], off offset:576
	v_pk_fma_f32 v[64:65], v[64:65], v[144:145], v[76:77]
	v_pk_fma_f32 v[62:63], v[62:63], v[142:143], v[74:75]
	s_waitcnt vmcnt(2)
	v_pk_fma_f32 v[44:45], v[56:57], v[144:145], v[92:93]
	v_pk_fma_f32 v[42:43], v[54:55], v[142:143], v[90:91]
	v_pk_fma_f32 v[60:61], v[60:61], v[140:141], v[68:69]
	v_pk_fma_f32 v[58:59], v[58:59], v[138:139], v[66:67]
	v_pk_fma_f32 v[52:53], v[52:53], v[136:137], v[72:73]
	v_pk_fma_f32 v[50:51], v[50:51], v[134:135], v[70:71]
	global_store_dwordx4 v[104:105], v[42:45], off
	v_pk_fma_f32 v[40:41], v[40:41], v[136:137], v[88:89]
	v_pk_fma_f32 v[38:39], v[38:39], v[134:135], v[86:87]
	v_pk_fma_f32 v[44:45], v[48:49], v[140:141], v[84:85]
	v_pk_fma_f32 v[42:43], v[46:47], v[138:139], v[82:83]
	s_waitcnt vmcnt(2)
	v_pk_fma_f32 v[36:37], v[36:37], v[132:133], v[96:97]
	v_pk_fma_f32 v[34:35], v[34:35], v[130:131], v[94:95]
	global_store_dwordx4 v[100:101], v[62:65], off
	global_store_dwordx4 v[98:99], v[58:61], off offset:64
	global_store_dwordx4 v[98:99], v[50:53], off offset:512
	global_store_dwordx4 v[102:103], v[42:45], off offset:64
	global_store_dwordx4 v[102:103], v[38:41], off offset:512
	global_store_dwordx4 v[102:103], v[34:37], off offset:576
	s_mov_b64 s[18:19], 0xa0000
	v_lshl_add_u64 v[66:67], v[152:153], 0, s[18:19]
	s_mov_b32 s18, 0xa0000
	v_add_co_u32_e32 v68, vcc, s18, v152
	s_mov_b64 s[18:19], 0xb0000
	s_nop 0
	v_addc_co_u32_e32 v69, vcc, 0, v153, vcc
	v_lshl_add_u64 v[70:71], v[152:153], 0, s[18:19]
	s_mov_b32 s18, 0xb0000
	v_add_co_u32_e32 v72, vcc, s18, v152
	global_load_dwordx4 v[34:37], v[66:67], off offset:64
	global_load_dwordx4 v[38:41], v[66:67], off offset:512
	global_load_dwordx4 v[42:45], v[68:69], off
	global_load_dwordx4 v[46:49], v[66:67], off offset:576
	v_addc_co_u32_e32 v73, vcc, 0, v153, vcc
	global_load_dwordx4 v[50:53], v[70:71], off offset:64
	global_load_dwordx4 v[54:57], v[70:71], off offset:512
	global_load_dwordx4 v[58:61], v[72:73], off
	global_load_dwordx4 v[62:65], v[70:71], off offset:576
	s_waitcnt vmcnt(4)
	v_pk_fma_f32 v[12:13], v[12:13], v[132:133], v[48:49]
	v_pk_fma_f32 v[10:11], v[10:11], v[130:131], v[46:47]
	global_store_dwordx4 v[66:67], v[10:13], off offset:576
	v_pk_fma_f32 v[32:33], v[32:33], v[144:145], v[44:45]
	v_pk_fma_f32 v[30:31], v[30:31], v[142:143], v[42:43]
	s_waitcnt vmcnt(2)
	v_pk_fma_f32 v[12:13], v[24:25], v[144:145], v[60:61]
	v_pk_fma_f32 v[10:11], v[22:23], v[142:143], v[58:59]
	v_pk_fma_f32 v[28:29], v[28:29], v[140:141], v[36:37]
	v_pk_fma_f32 v[26:27], v[26:27], v[138:139], v[34:35]
	v_pk_fma_f32 v[20:21], v[20:21], v[136:137], v[40:41]
	v_pk_fma_f32 v[18:19], v[18:19], v[134:135], v[38:39]
	global_store_dwordx4 v[72:73], v[10:13], off
	v_pk_fma_f32 v[8:9], v[8:9], v[136:137], v[56:57]
	v_pk_fma_f32 v[6:7], v[6:7], v[134:135], v[54:55]
	v_pk_fma_f32 v[12:13], v[16:17], v[140:141], v[52:53]
	v_pk_fma_f32 v[10:11], v[14:15], v[138:139], v[50:51]
	s_waitcnt vmcnt(2)
	v_pk_fma_f32 v[4:5], v[4:5], v[132:133], v[64:65]
	v_pk_fma_f32 v[2:3], v[2:3], v[130:131], v[62:63]
	global_store_dwordx4 v[68:69], v[30:33], off
	global_store_dwordx4 v[66:67], v[26:29], off offset:64
	global_store_dwordx4 v[66:67], v[18:21], off offset:512
	global_store_dwordx4 v[70:71], v[10:13], off offset:64
	global_store_dwordx4 v[70:71], v[6:9], off offset:512
	global_store_dwordx4 v[70:71], v[2:5], off offset:576
	v_readlane_b32 s66, v255, 2
	s_and_b64 vcc, exec, s[6:7]
	s_mov_b64 s[6:7], -1
	v_readlane_b32 s67, v255, 3
	s_cbranch_vccnz .LBB0_107
	s_andn2_b64 vcc, exec, s[12:13]
	s_cbranch_vccnz .LBB0_106
	s_barrier
	s_branch .LBB0_106

.LBB0_238:
	s_ashr_i32 s21, s76, 31
	s_sub_i32 s23, s76, 64
	s_cmp_gt_i32 s76, 63
	v_readlane_b32 s38, v255, 52
	s_cselect_b32 s29, 0, s21
	s_cselect_b32 s28, s23, s76
	v_readlane_b32 s39, v255, 53
	s_cselect_b32 s21, s11, s13
	s_cselect_b32 s23, s10, s12
	s_cselect_b32 s44, s39, s15
	s_cselect_b32 s45, s38, s14
	s_lshl_b64 s[28:29], s[28:29], 20
	s_add_u32 s38, s23, s28
	s_addc_u32 s39, s21, s29
	s_add_u32 s28, s45, s28
	s_addc_u32 s29, s44, s29
	s_min_i32 s21, s76, 64
	s_lshr_b32 s21, s21, 4
	s_mul_i32 s44, s21, 0x1800
	s_ashr_i32 s45, s44, 31
	s_lshl_b64 s[44:45], s[44:45], 2
	v_mov_b32_e32 v154, v191
	s_add_u32 s44, s49, s44
	s_addc_u32 s45, s56, s45
	s_lshl_b32 s21, s74, 8
	v_lshrrev_b32_e32 v130, 2, v154
	v_and_or_b32 v130, v130, 12, s21
	v_or_b32_e32 v130, s66, v130
	v_and_or_b32 v188, v154, 15, s57
	v_ashrrev_i32_e32 v131, 31, v130
	v_or_b32_e32 v176, 16, v188
	v_lshlrev_b64 v[152:153], 2, v[130:131]
	v_ashrrev_i32_e32 v189, 31, v188
	v_ashrrev_i32_e32 v177, 31, v176
	v_lshl_add_u64 v[154:155], s[38:39], 0, v[152:153]
	v_lshlrev_b64 v[156:157], 12, v[188:189]
	v_lshlrev_b64 v[192:193], 12, v[176:177]
	v_lshl_add_u64 v[130:131], s[44:45], 0, v[152:153]
	v_lshl_add_u64 v[172:173], v[154:155], 0, v[156:157]
	v_lshl_add_u64 v[194:195], v[154:155], 0, v[192:193]
	global_load_dwordx4 v[142:145], v[130:131], off
	global_load_dwordx4 v[138:141], v[130:131], off offset:64
	global_load_dwordx4 v[134:137], v[130:131], off offset:512
	s_nop 0
	global_load_dwordx4 v[130:133], v[130:131], off offset:576
	s_nop 0
	global_load_dwordx4 v[160:163], v[172:173], off
	global_load_dwordx4 v[164:167], v[172:173], off offset:64
	global_load_dwordx4 v[168:171], v[172:173], off offset:512
	s_nop 0
	global_load_dwordx4 v[172:175], v[172:173], off offset:576
	s_waitcnt vmcnt(0)
	s_nop 0
	global_load_dwordx4 v[176:179], v[194:195], off
	global_load_dwordx4 v[180:183], v[194:195], off offset:64
	global_load_dwordx4 v[184:187], v[194:195], off offset:512
	global_load_dwordx4 v[196:199], v[194:195], off offset:576
	v_lshl_add_u64 v[152:153], s[28:29], 0, v[152:153]
	v_lshl_add_u64 v[194:195], v[152:153], 0, v[156:157]
	s_waitcnt vmcnt(0)
	v_pk_fma_f32 v[120:121], v[120:121], v[136:137], v[170:171]
	v_pk_fma_f32 v[118:119], v[118:119], v[134:135], v[168:169]
	v_pk_fma_f32 v[108:109], v[108:109], v[132:133], v[174:175]
	v_pk_fma_f32 v[106:107], v[106:107], v[130:131], v[172:173]
	global_store_dwordx4 v[194:195], v[118:121], off offset:512
	global_store_dwordx4 v[194:195], v[106:109], off offset:576
	v_pk_fma_f32 v[128:129], v[128:129], v[144:145], v[162:163]
	v_lshl_add_u64 v[118:119], v[152:153], 0, v[192:193]
	v_pk_fma_f32 v[108:109], v[116:117], v[144:145], v[178:179]
	v_pk_fma_f32 v[106:107], v[114:115], v[142:143], v[176:177]
	v_pk_fma_f32 v[126:127], v[126:127], v[142:143], v[160:161]
	v_pk_fma_f32 v[124:125], v[124:125], v[140:141], v[166:167]
	v_pk_fma_f32 v[122:123], v[122:123], v[138:139], v[164:165]
	global_store_dwordx4 v[118:119], v[106:109], off
	v_pk_fma_f32 v[104:105], v[104:105], v[136:137], v[186:187]
	v_pk_fma_f32 v[102:103], v[102:103], v[134:135], v[184:185]
	v_pk_fma_f32 v[108:109], v[112:113], v[140:141], v[182:183]
	v_pk_fma_f32 v[106:107], v[110:111], v[138:139], v[180:181]
	v_pk_fma_f32 v[100:101], v[100:101], v[132:133], v[198:199]
	v_pk_fma_f32 v[98:99], v[98:99], v[130:131], v[196:197]
	global_store_dwordx4 v[194:195], v[126:129], off
	global_store_dwordx4 v[194:195], v[122:125], off offset:64
	global_store_dwordx4 v[118:119], v[106:109], off offset:64
	global_store_dwordx4 v[118:119], v[102:105], off offset:512
	global_store_dwordx4 v[118:119], v[98:101], off offset:576
	s_nop 1
	v_or_b32_e32 v98, 32, v188
	v_or_b32_e32 v114, 48, v188
	v_ashrrev_i32_e32 v99, 31, v98
	v_ashrrev_i32_e32 v115, 31, v114
	v_lshlrev_b64 v[160:161], 12, v[98:99]
	v_lshlrev_b64 v[162:163], 12, v[114:115]
	v_lshl_add_u64 v[110:111], v[154:155], 0, v[160:161]
	v_lshl_add_u64 v[126:127], v[154:155], 0, v[162:163]
	global_load_dwordx4 v[98:101], v[110:111], off
	global_load_dwordx4 v[102:105], v[110:111], off offset:64
	global_load_dwordx4 v[106:109], v[110:111], off offset:512
	s_nop 0
	global_load_dwordx4 v[110:113], v[110:111], off offset:576
	s_waitcnt vmcnt(0)
	s_nop 0
	global_load_dwordx4 v[114:117], v[126:127], off
	global_load_dwordx4 v[118:121], v[126:127], off offset:64
	global_load_dwordx4 v[122:125], v[126:127], off offset:512
	s_nop 0
	global_load_dwordx4 v[126:129], v[126:127], off offset:576
	v_lshl_add_u64 v[160:161], v[152:153], 0, v[160:161]
	s_waitcnt vmcnt(5)
	v_pk_fma_f32 v[84:85], v[84:85], v[136:137], v[108:109]
	v_pk_fma_f32 v[82:83], v[82:83], v[134:135], v[106:107]
	s_waitcnt vmcnt(4)
	v_pk_fma_f32 v[76:77], v[76:77], v[132:133], v[112:113]
	v_pk_fma_f32 v[74:75], v[74:75], v[130:131], v[110:111]
	global_store_dwordx4 v[160:161], v[82:85], off offset:512
	global_store_dwordx4 v[160:161], v[74:77], off offset:576
	v_pk_fma_f32 v[96:97], v[96:97], v[144:145], v[100:101]
	v_lshl_add_u64 v[82:83], v[152:153], 0, v[162:163]
	s_waitcnt vmcnt(5)
	v_pk_fma_f32 v[76:77], v[88:89], v[144:145], v[116:117]
	v_pk_fma_f32 v[74:75], v[86:87], v[142:143], v[114:115]
	v_pk_fma_f32 v[94:95], v[94:95], v[142:143], v[98:99]
	v_pk_fma_f32 v[92:93], v[92:93], v[140:141], v[104:105]
	v_pk_fma_f32 v[90:91], v[90:91], v[138:139], v[102:103]
	global_store_dwordx4 v[82:83], v[74:77], off
	s_waitcnt vmcnt(4)
	v_pk_fma_f32 v[72:73], v[72:73], v[136:137], v[124:125]
	v_pk_fma_f32 v[70:71], v[70:71], v[134:135], v[122:123]
	v_pk_fma_f32 v[76:77], v[80:81], v[140:141], v[120:121]
	v_pk_fma_f32 v[74:75], v[78:79], v[138:139], v[118:119]
	s_waitcnt vmcnt(3)
	v_pk_fma_f32 v[68:69], v[68:69], v[132:133], v[128:129]
	v_pk_fma_f32 v[66:67], v[66:67], v[130:131], v[126:127]
	global_store_dwordx4 v[160:161], v[94:97], off
	global_store_dwordx4 v[160:161], v[90:93], off offset:64
	global_store_dwordx4 v[82:83], v[74:77], off offset:64
	global_store_dwordx4 v[82:83], v[70:73], off offset:512
	global_store_dwordx4 v[82:83], v[66:69], off offset:576
	s_mov_b64 s[28:29], 0x80000
	v_lshl_add_u64 v[98:99], v[156:157], 0, s[28:29]
	s_mov_b64 s[28:29], 0x90000
	v_lshl_add_u64 v[100:101], v[156:157], 0, s[28:29]
	v_lshl_add_u64 v[78:79], v[154:155], 0, v[98:99]
	v_lshl_add_u64 v[94:95], v[154:155], 0, v[100:101]
	global_load_dwordx4 v[66:69], v[78:79], off
	global_load_dwordx4 v[70:73], v[78:79], off offset:64
	global_load_dwordx4 v[74:77], v[78:79], off offset:512
	s_nop 0
	global_load_dwordx4 v[78:81], v[78:79], off offset:576
	s_waitcnt vmcnt(0)
	s_nop 0
	global_load_dwordx4 v[82:85], v[94:95], off
	global_load_dwordx4 v[86:89], v[94:95], off offset:64
	global_load_dwordx4 v[90:93], v[94:95], off offset:512
	s_nop 0
	global_load_dwordx4 v[94:97], v[94:95], off offset:576
	v_lshl_add_u64 v[98:99], v[152:153], 0, v[98:99]
	s_waitcnt vmcnt(5)
	v_pk_fma_f32 v[52:53], v[52:53], v[136:137], v[76:77]
	v_pk_fma_f32 v[50:51], v[50:51], v[134:135], v[74:75]
	s_waitcnt vmcnt(4)
	v_pk_fma_f32 v[44:45], v[44:45], v[132:133], v[80:81]
	v_pk_fma_f32 v[42:43], v[42:43], v[130:131], v[78:79]
	global_store_dwordx4 v[98:99], v[50:53], off offset:512
	global_store_dwordx4 v[98:99], v[42:45], off offset:576
	v_pk_fma_f32 v[64:65], v[64:65], v[144:145], v[68:69]
	v_lshl_add_u64 v[50:51], v[152:153], 0, v[100:101]
	s_waitcnt vmcnt(5)
	v_pk_fma_f32 v[44:45], v[56:57], v[144:145], v[84:85]
	v_pk_fma_f32 v[42:43], v[54:55], v[142:143], v[82:83]
	v_pk_fma_f32 v[62:63], v[62:63], v[142:143], v[66:67]
	v_pk_fma_f32 v[60:61], v[60:61], v[140:141], v[72:73]
	v_pk_fma_f32 v[58:59], v[58:59], v[138:139], v[70:71]
	global_store_dwordx4 v[50:51], v[42:45], off
	s_waitcnt vmcnt(4)
	v_pk_fma_f32 v[40:41], v[40:41], v[136:137], v[92:93]
	v_pk_fma_f32 v[38:39], v[38:39], v[134:135], v[90:91]
	v_pk_fma_f32 v[44:45], v[48:49], v[140:141], v[88:89]
	v_pk_fma_f32 v[42:43], v[46:47], v[138:139], v[86:87]
	s_waitcnt vmcnt(3)
	v_pk_fma_f32 v[32:33], v[32:33], v[132:133], v[96:97]
	v_pk_fma_f32 v[30:31], v[30:31], v[130:131], v[94:95]
	global_store_dwordx4 v[98:99], v[62:65], off
	global_store_dwordx4 v[98:99], v[58:61], off offset:64
	global_store_dwordx4 v[50:51], v[42:45], off offset:64
	global_store_dwordx4 v[50:51], v[38:41], off offset:512
	global_store_dwordx4 v[50:51], v[30:33], off offset:576
	s_mov_b64 s[28:29], 0xa0000
	v_lshl_add_u64 v[66:67], v[156:157], 0, s[28:29]
	s_mov_b64 s[28:29], 0xb0000
	v_lshl_add_u64 v[68:69], v[156:157], 0, s[28:29]
	v_lshl_add_u64 v[46:47], v[154:155], 0, v[66:67]
	v_lshl_add_u64 v[62:63], v[154:155], 0, v[68:69]
	global_load_dwordx4 v[30:33], v[46:47], off
	global_load_dwordx4 v[38:41], v[46:47], off offset:64
	global_load_dwordx4 v[42:45], v[46:47], off offset:512
	s_nop 0
	global_load_dwordx4 v[46:49], v[46:47], off offset:576
	s_waitcnt vmcnt(0)
	s_nop 0
	global_load_dwordx4 v[50:53], v[62:63], off
	global_load_dwordx4 v[54:57], v[62:63], off offset:64
	global_load_dwordx4 v[58:61], v[62:63], off offset:512
	s_nop 0
	global_load_dwordx4 v[62:65], v[62:63], off offset:576
	v_lshl_add_u64 v[66:67], v[152:153], 0, v[66:67]
	s_waitcnt vmcnt(5)
	v_pk_fma_f32 v[20:21], v[20:21], v[136:137], v[44:45]
	v_pk_fma_f32 v[18:19], v[18:19], v[134:135], v[42:43]
	s_waitcnt vmcnt(4)
	v_pk_fma_f32 v[12:13], v[12:13], v[132:133], v[48:49]
	v_pk_fma_f32 v[10:11], v[10:11], v[130:131], v[46:47]
	global_store_dwordx4 v[66:67], v[18:21], off offset:512
	global_store_dwordx4 v[66:67], v[10:13], off offset:576
	v_pk_fma_f32 v[32:33], v[36:37], v[144:145], v[32:33]
	v_lshl_add_u64 v[18:19], v[152:153], 0, v[68:69]
	s_waitcnt vmcnt(5)
	v_pk_fma_f32 v[12:13], v[24:25], v[144:145], v[52:53]
	v_pk_fma_f32 v[10:11], v[22:23], v[142:143], v[50:51]
	v_pk_fma_f32 v[30:31], v[34:35], v[142:143], v[30:31]
	v_pk_fma_f32 v[28:29], v[28:29], v[140:141], v[40:41]
	v_pk_fma_f32 v[26:27], v[26:27], v[138:139], v[38:39]
	global_store_dwordx4 v[18:19], v[10:13], off
	s_waitcnt vmcnt(4)
	v_pk_fma_f32 v[8:9], v[8:9], v[136:137], v[60:61]
	v_pk_fma_f32 v[6:7], v[6:7], v[134:135], v[58:59]
	v_pk_fma_f32 v[12:13], v[16:17], v[140:141], v[56:57]
	v_pk_fma_f32 v[10:11], v[14:15], v[138:139], v[54:55]
	s_waitcnt vmcnt(3)
	v_pk_fma_f32 v[4:5], v[4:5], v[132:133], v[64:65]
	v_pk_fma_f32 v[2:3], v[2:3], v[130:131], v[62:63]
	global_store_dwordx4 v[66:67], v[30:33], off
	global_store_dwordx4 v[66:67], v[26:29], off offset:64
	global_store_dwordx4 v[18:19], v[10:13], off offset:64
	global_store_dwordx4 v[18:19], v[6:9], off offset:512
	global_store_dwordx4 v[18:19], v[2:5], off offset:576
	s_andn2_b64 vcc, exec, s[8:9]
	s_mov_b64 s[8:9], -1
	v_readlane_b32 s81, v254, 62
	s_mov_b32 s93, 0x38000
	s_cbranch_vccnz .LBB0_227
	s_andn2_b64 vcc, exec, s[16:17]
	s_cbranch_vccnz .LBB0_226
	s_barrier
	s_branch .LBB0_226
